# RWKV static scan loop refined: straight-line 32-step tile (no back-edge), no beyond-tile LDS prefetch in last block, one lgkmcnt wait per two steps
# speedup vs baseline: 1.0476x; 1.0085x over previous
.LrwT_tile:
	s_and_b32 s30, s26, 1
	s_waitcnt vmcnt(0)
	s_lshl_b32 s36, s30, 11
	s_lshl_b32 s37, s30, 15
	v_or_b32_e32 v30, s37, v69
	v_add_u32_e32 v49, s36, v92
	v_add_u32_e32 v1, s36, v94
	v_cndmask_b32_e64 v53, v93, v1, s[24:25]
	v_lshl_add_u32 v0, s30, 8, v95
	ds_read_b128 v[168:171], v30
	ds_read_b128 v[172:175], v30 offset:256
	ds_read_b128 v[176:179], v30 offset:512
	ds_read_b128 v[180:183], v30 offset:768
	ds_read_b128 v[64:67], v49
	ds_read_b128 v[184:187], v30 offset:1024
	ds_read_b128 v[188:191], v30 offset:1280
	ds_read_b128 v[192:195], v30 offset:1536
	ds_read_b128 v[196:199], v30 offset:1792
	ds_read_b128 v[200:203], v30 offset:2048
	ds_read_b128 v[204:207], v30 offset:2304
	ds_read_b128 v[208:211], v30 offset:2560
	ds_read_b128 v[212:215], v30 offset:2816
	ds_read_b128 v[108:111], v0
	s_lshl_b32 s27, s26, 5
	s_sub_i32 s27, 0x4010, s27
	s_min_u32 s27, s27, 32
	s_lshr_b32 s36, s27, 3
	s_waitcnt lgkmcnt(5)
	v_pk_mul_f32 v[0:1], v[16:17], v[176:177]
	v_pk_fma_f32 v[12:13], v[64:65], v[172:173], v[16:17] op_sel_hi:[0,1,1]
	v_pk_fma_f32 v[0:1], v[18:19], v[178:179], v[0:1]
	v_pk_fma_f32 v[14:15], v[64:65], v[174:175], v[18:19] op_sel_hi:[0,1,1]
	v_add_f32_e32 v2, v0, v1
	ds_read_b128 v[216:219], v30 offset:3072
	ds_read_b128 v[220:223], v30 offset:3328
	v_add_f32_dpp v2, v2, v2 quad_perm:[1,0,3,2] row_mask:0xf bank_mask:0xf bound_ctrl:1
	ds_read_b128 v[224:227], v30 offset:3584
	ds_read_b128 v[228:231], v30 offset:3840
	v_add_f32_dpp v2, v2, v2 quad_perm:[2,3,0,1] row_mask:0xf bank_mask:0xf bound_ctrl:1
	s_nop 0
	s_nop 0
	v_add_f32_dpp v2, v2, v2 row_half_mirror row_mask:0xf bank_mask:0xf bound_ctrl:1
	s_nop 0
	s_nop 0
	v_add_f32_dpp v2, v2, v2 row_mirror row_mask:0xf bank_mask:0xf bound_ctrl:1
	ds_read_b128 v[104:107], v49 offset:16
	v_pk_fma_f32 v[12:13], v[2:3], v[180:181], v[12:13] op_sel_hi:[0,1,1] neg_lo:[1,0,0] neg_hi:[1,0,0]
	v_pk_fma_f32 v[14:15], v[2:3], v[182:183], v[14:15] op_sel_hi:[0,1,1] neg_lo:[1,0,0] neg_hi:[1,0,0]
	v_pk_mul_f32 v[0:1], v[12:13], v[192:193]
	v_pk_fma_f32 v[16:17], v[64:65], v[188:189], v[12:13] op_sel:[1,0,0]
	v_pk_fma_f32 v[0:1], v[14:15], v[194:195], v[0:1]
	v_pk_fma_f32 v[18:19], v[64:65], v[190:191], v[14:15] op_sel:[1,0,0]
	v_add_f32_e32 v2, v0, v1
	v_pk_mul_f32 v[4:5], v[168:169], v[12:13]
	v_pk_fma_f32 v[4:5], v[14:15], v[170:171], v[4:5]
	v_add_f32_dpp v2, v2, v2 quad_perm:[1,0,3,2] row_mask:0xf bank_mask:0xf bound_ctrl:1
	v_add_f32_e32 v8, v4, v5
	ds_read_b128 v[168:171], v30 offset:4096
	v_add_f32_dpp v2, v2, v2 quad_perm:[2,3,0,1] row_mask:0xf bank_mask:0xf bound_ctrl:1
	ds_read_b128 v[172:175], v30 offset:4352
	ds_read_b128 v[176:179], v30 offset:4608
	v_add_f32_dpp v2, v2, v2 row_half_mirror row_mask:0xf bank_mask:0xf bound_ctrl:1
	ds_read_b128 v[180:183], v30 offset:4864
	s_nop 0
	v_add_f32_dpp v2, v2, v2 row_mirror row_mask:0xf bank_mask:0xf bound_ctrl:1
	s_nop 0
	v_pk_fma_f32 v[16:17], v[2:3], v[196:197], v[16:17] op_sel_hi:[0,1,1] neg_lo:[1,0,0] neg_hi:[1,0,0]
	v_pk_fma_f32 v[18:19], v[2:3], v[198:199], v[18:19] op_sel_hi:[0,1,1] neg_lo:[1,0,0] neg_hi:[1,0,0]
	s_waitcnt lgkmcnt(5)
	v_pk_mul_f32 v[0:1], v[16:17], v[208:209]
	v_pk_fma_f32 v[12:13], v[66:67], v[204:205], v[16:17] op_sel_hi:[0,1,1]
	v_pk_fma_f32 v[0:1], v[18:19], v[210:211], v[0:1]
	v_pk_fma_f32 v[14:15], v[66:67], v[206:207], v[18:19] op_sel_hi:[0,1,1]
	v_add_f32_e32 v2, v0, v1
	v_pk_mul_f32 v[4:5], v[184:185], v[16:17]
	v_pk_fma_f32 v[4:5], v[18:19], v[186:187], v[4:5]
	v_add_f32_dpp v2, v2, v2 quad_perm:[1,0,3,2] row_mask:0xf bank_mask:0xf bound_ctrl:1
	v_add_f32_e32 v9, v4, v5
	ds_read_b128 v[184:187], v30 offset:5120
	v_add_f32_dpp v2, v2, v2 quad_perm:[2,3,0,1] row_mask:0xf bank_mask:0xf bound_ctrl:1
	ds_read_b128 v[188:191], v30 offset:5376
	ds_read_b128 v[192:195], v30 offset:5632
	v_add_f32_dpp v2, v2, v2 row_half_mirror row_mask:0xf bank_mask:0xf bound_ctrl:1
	ds_read_b128 v[196:199], v30 offset:5888
	s_nop 0
	v_add_f32_dpp v2, v2, v2 row_mirror row_mask:0xf bank_mask:0xf bound_ctrl:1
	s_nop 0
	v_pk_fma_f32 v[12:13], v[2:3], v[212:213], v[12:13] op_sel_hi:[0,1,1] neg_lo:[1,0,0] neg_hi:[1,0,0]
	v_pk_fma_f32 v[14:15], v[2:3], v[214:215], v[14:15] op_sel_hi:[0,1,1] neg_lo:[1,0,0] neg_hi:[1,0,0]
	v_pk_mul_f32 v[0:1], v[12:13], v[224:225]
	v_pk_fma_f32 v[16:17], v[66:67], v[220:221], v[12:13] op_sel:[1,0,0]
	v_pk_fma_f32 v[0:1], v[14:15], v[226:227], v[0:1]
	v_pk_fma_f32 v[18:19], v[66:67], v[222:223], v[14:15] op_sel:[1,0,0]
	v_add_f32_e32 v2, v0, v1
	v_pk_mul_f32 v[4:5], v[200:201], v[12:13]
	v_pk_fma_f32 v[4:5], v[14:15], v[202:203], v[4:5]
	v_add_f32_dpp v2, v2, v2 quad_perm:[1,0,3,2] row_mask:0xf bank_mask:0xf bound_ctrl:1
	v_add_f32_e32 v10, v4, v5
	ds_read_b128 v[200:203], v30 offset:6144
	v_add_f32_dpp v2, v2, v2 quad_perm:[2,3,0,1] row_mask:0xf bank_mask:0xf bound_ctrl:1
	ds_read_b128 v[204:207], v30 offset:6400
	ds_read_b128 v[208:211], v30 offset:6656
	v_add_f32_dpp v2, v2, v2 row_half_mirror row_mask:0xf bank_mask:0xf bound_ctrl:1
	ds_read_b128 v[212:215], v30 offset:6912
	s_nop 0
	v_add_f32_dpp v2, v2, v2 row_mirror row_mask:0xf bank_mask:0xf bound_ctrl:1
	s_nop 0
	v_pk_fma_f32 v[16:17], v[2:3], v[228:229], v[16:17] op_sel_hi:[0,1,1] neg_lo:[1,0,0] neg_hi:[1,0,0]
	v_pk_fma_f32 v[18:19], v[2:3], v[230:231], v[18:19] op_sel_hi:[0,1,1] neg_lo:[1,0,0] neg_hi:[1,0,0]
	s_waitcnt lgkmcnt(4)
	v_pk_mul_f32 v[0:1], v[16:17], v[176:177]
	v_pk_fma_f32 v[12:13], v[104:105], v[172:173], v[16:17] op_sel_hi:[0,1,1]
	v_pk_fma_f32 v[0:1], v[18:19], v[178:179], v[0:1]
	v_pk_fma_f32 v[14:15], v[104:105], v[174:175], v[18:19] op_sel_hi:[0,1,1]
	v_add_f32_e32 v2, v0, v1
	v_pk_mul_f32 v[4:5], v[216:217], v[16:17]
	v_pk_fma_f32 v[4:5], v[18:19], v[218:219], v[4:5]
	v_add_f32_dpp v2, v2, v2 quad_perm:[1,0,3,2] row_mask:0xf bank_mask:0xf bound_ctrl:1
	v_add_f32_e32 v11, v4, v5
	ds_read_b128 v[216:219], v30 offset:7168
	v_add_f32_dpp v2, v2, v2 quad_perm:[2,3,0,1] row_mask:0xf bank_mask:0xf bound_ctrl:1
	ds_read_b128 v[220:223], v30 offset:7424
	ds_read_b128 v[224:227], v30 offset:7680
	v_add_f32_dpp v2, v2, v2 row_half_mirror row_mask:0xf bank_mask:0xf bound_ctrl:1
	ds_read_b128 v[228:231], v30 offset:7936
	v_cndmask_b32_e64 v6, v9, v8, s[12:13]
	v_add_f32_dpp v2, v2, v2 row_mirror row_mask:0xf bank_mask:0xf bound_ctrl:1
	v_cndmask_b32_e64 v7, v8, v9, s[12:13]
	v_cndmask_b32_e64 v55, v11, v10, s[12:13]
	v_cndmask_b32_e64 v57, v10, v11, s[12:13]
	v_pk_fma_f32 v[12:13], v[2:3], v[180:181], v[12:13] op_sel_hi:[0,1,1] neg_lo:[1,0,0] neg_hi:[1,0,0]
	v_pk_fma_f32 v[14:15], v[2:3], v[182:183], v[14:15] op_sel_hi:[0,1,1] neg_lo:[1,0,0] neg_hi:[1,0,0]
	v_pk_mul_f32 v[0:1], v[12:13], v[192:193]
	v_pk_fma_f32 v[16:17], v[104:105], v[188:189], v[12:13] op_sel:[1,0,0]
	v_pk_fma_f32 v[0:1], v[14:15], v[194:195], v[0:1]
	v_pk_fma_f32 v[18:19], v[104:105], v[190:191], v[14:15] op_sel:[1,0,0]
	v_add_f32_e32 v2, v0, v1
	v_pk_mul_f32 v[4:5], v[168:169], v[12:13]
	v_pk_fma_f32 v[4:5], v[14:15], v[170:171], v[4:5]
	v_add_f32_dpp v2, v2, v2 quad_perm:[1,0,3,2] row_mask:0xf bank_mask:0xf bound_ctrl:1
	v_add_f32_e32 v24, v4, v5
	ds_read_b128 v[168:171], v30 offset:8192
	v_add_f32_dpp v2, v2, v2 quad_perm:[2,3,0,1] row_mask:0xf bank_mask:0xf bound_ctrl:1
	ds_read_b128 v[172:175], v30 offset:8448
	ds_read_b128 v[176:179], v30 offset:8704
	v_add_f32_dpp v2, v2, v2 row_half_mirror row_mask:0xf bank_mask:0xf bound_ctrl:1
	ds_read_b128 v[180:183], v30 offset:8960
	v_add_f32_dpp v6, v7, v6 quad_perm:[1,0,3,2] row_mask:0xf bank_mask:0xf bound_ctrl:1
	v_add_f32_dpp v2, v2, v2 row_mirror row_mask:0xf bank_mask:0xf bound_ctrl:1
	v_add_f32_dpp v55, v57, v55 quad_perm:[1,0,3,2] row_mask:0xf bank_mask:0xf bound_ctrl:1
	v_cndmask_b32_e64 v57, v6, v55, s[14:15]
	v_cndmask_b32_e64 v7, v55, v6, s[14:15]
	v_pk_fma_f32 v[16:17], v[2:3], v[196:197], v[16:17] op_sel_hi:[0,1,1] neg_lo:[1,0,0] neg_hi:[1,0,0]
	v_pk_fma_f32 v[18:19], v[2:3], v[198:199], v[18:19] op_sel_hi:[0,1,1] neg_lo:[1,0,0] neg_hi:[1,0,0]
	s_waitcnt lgkmcnt(4)
	v_pk_mul_f32 v[0:1], v[16:17], v[208:209]
	v_pk_fma_f32 v[12:13], v[106:107], v[204:205], v[16:17] op_sel_hi:[0,1,1]
	v_pk_fma_f32 v[0:1], v[18:19], v[210:211], v[0:1]
	v_pk_fma_f32 v[14:15], v[106:107], v[206:207], v[18:19] op_sel_hi:[0,1,1]
	v_add_f32_e32 v2, v0, v1
	v_pk_mul_f32 v[4:5], v[184:185], v[16:17]
	v_pk_fma_f32 v[4:5], v[18:19], v[186:187], v[4:5]
	v_add_f32_dpp v2, v2, v2 quad_perm:[1,0,3,2] row_mask:0xf bank_mask:0xf bound_ctrl:1
	v_add_f32_e32 v25, v4, v5
	ds_read_b128 v[184:187], v30 offset:9216
	v_add_f32_dpp v2, v2, v2 quad_perm:[2,3,0,1] row_mask:0xf bank_mask:0xf bound_ctrl:1
	ds_read_b128 v[188:191], v30 offset:9472
	ds_read_b128 v[192:195], v30 offset:9728
	v_add_f32_dpp v2, v2, v2 row_half_mirror row_mask:0xf bank_mask:0xf bound_ctrl:1
	ds_read_b128 v[196:199], v30 offset:9984
	v_add_f32_dpp v7, v57, v7 quad_perm:[2,3,0,1] row_mask:0xf bank_mask:0xf bound_ctrl:1
	v_add_f32_dpp v2, v2, v2 row_mirror row_mask:0xf bank_mask:0xf bound_ctrl:1
	ds_read_b128 v[64:67], v49 offset:32
	v_add_u32_e32 v49, 32, v49
	v_add_f32_dpp v7, v7, v7 row_ror:4 row_mask:0xf bank_mask:0xf bound_ctrl:1
	v_pk_fma_f32 v[12:13], v[2:3], v[212:213], v[12:13] op_sel_hi:[0,1,1] neg_lo:[1,0,0] neg_hi:[1,0,0]
	v_pk_fma_f32 v[14:15], v[2:3], v[214:215], v[14:15] op_sel_hi:[0,1,1] neg_lo:[1,0,0] neg_hi:[1,0,0]
	v_pk_mul_f32 v[0:1], v[12:13], v[224:225]
	v_pk_fma_f32 v[16:17], v[106:107], v[220:221], v[12:13] op_sel:[1,0,0]
	v_pk_fma_f32 v[0:1], v[14:15], v[226:227], v[0:1]
	v_pk_fma_f32 v[18:19], v[106:107], v[222:223], v[14:15] op_sel:[1,0,0]
	v_add_f32_e32 v2, v0, v1
	v_pk_mul_f32 v[4:5], v[200:201], v[12:13]
	v_pk_fma_f32 v[4:5], v[14:15], v[202:203], v[4:5]
	v_add_f32_dpp v2, v2, v2 quad_perm:[1,0,3,2] row_mask:0xf bank_mask:0xf bound_ctrl:1
	v_add_f32_e32 v26, v4, v5
	ds_read_b128 v[200:203], v30 offset:10240
	v_add_f32_dpp v2, v2, v2 quad_perm:[2,3,0,1] row_mask:0xf bank_mask:0xf bound_ctrl:1
	ds_read_b128 v[204:207], v30 offset:10496
	ds_read_b128 v[208:211], v30 offset:10752
	v_add_f32_dpp v2, v2, v2 row_half_mirror row_mask:0xf bank_mask:0xf bound_ctrl:1
	ds_read_b128 v[212:215], v30 offset:11008
	v_add_f32_dpp v7, v7, v7 row_ror:8 row_mask:0xf bank_mask:0xf bound_ctrl:1
	v_add_f32_dpp v2, v2, v2 row_mirror row_mask:0xf bank_mask:0xf bound_ctrl:1
	ds_write_b32 v53, v7
	v_pk_fma_f32 v[16:17], v[2:3], v[228:229], v[16:17] op_sel_hi:[0,1,1] neg_lo:[1,0,0] neg_hi:[1,0,0]
	v_pk_fma_f32 v[18:19], v[2:3], v[230:231], v[18:19] op_sel_hi:[0,1,1] neg_lo:[1,0,0] neg_hi:[1,0,0]
	v_add_u32_e32 v30, 0x2000, v30
	s_cmp_eq_u32 s36, 2
	s_cbranch_scc1 .LrwT_last
	s_waitcnt lgkmcnt(5)
	v_pk_mul_f32 v[0:1], v[16:17], v[176:177]
	v_pk_fma_f32 v[12:13], v[64:65], v[172:173], v[16:17] op_sel_hi:[0,1,1]
	v_pk_fma_f32 v[0:1], v[18:19], v[178:179], v[0:1]
	v_pk_fma_f32 v[14:15], v[64:65], v[174:175], v[18:19] op_sel_hi:[0,1,1]
	v_add_f32_e32 v2, v0, v1
	v_pk_mul_f32 v[4:5], v[216:217], v[16:17]
	v_pk_fma_f32 v[4:5], v[18:19], v[218:219], v[4:5]
	v_add_f32_dpp v2, v2, v2 quad_perm:[1,0,3,2] row_mask:0xf bank_mask:0xf bound_ctrl:1
	v_add_f32_e32 v27, v4, v5
	ds_read_b128 v[216:219], v30 offset:3072
	v_add_f32_dpp v2, v2, v2 quad_perm:[2,3,0,1] row_mask:0xf bank_mask:0xf bound_ctrl:1
	ds_read_b128 v[220:223], v30 offset:3328
	ds_read_b128 v[224:227], v30 offset:3584
	v_add_f32_dpp v2, v2, v2 row_half_mirror row_mask:0xf bank_mask:0xf bound_ctrl:1
	ds_read_b128 v[228:231], v30 offset:3840
	v_cndmask_b32_e64 v6, v25, v24, s[12:13]
	v_add_f32_dpp v2, v2, v2 row_mirror row_mask:0xf bank_mask:0xf bound_ctrl:1
	v_cndmask_b32_e64 v7, v24, v25, s[12:13]
	v_cndmask_b32_e64 v55, v27, v26, s[12:13]
	v_cndmask_b32_e64 v57, v26, v27, s[12:13]
	v_pk_fma_f32 v[12:13], v[2:3], v[180:181], v[12:13] op_sel_hi:[0,1,1] neg_lo:[1,0,0] neg_hi:[1,0,0]
	v_pk_fma_f32 v[14:15], v[2:3], v[182:183], v[14:15] op_sel_hi:[0,1,1] neg_lo:[1,0,0] neg_hi:[1,0,0]
	v_pk_mul_f32 v[0:1], v[12:13], v[192:193]
	v_pk_fma_f32 v[16:17], v[64:65], v[188:189], v[12:13] op_sel:[1,0,0]
	v_pk_fma_f32 v[0:1], v[14:15], v[194:195], v[0:1]
	v_pk_fma_f32 v[18:19], v[64:65], v[190:191], v[14:15] op_sel:[1,0,0]
	v_add_f32_e32 v2, v0, v1
	v_pk_mul_f32 v[4:5], v[168:169], v[12:13]
	v_pk_fma_f32 v[4:5], v[14:15], v[170:171], v[4:5]
	v_add_f32_dpp v2, v2, v2 quad_perm:[1,0,3,2] row_mask:0xf bank_mask:0xf bound_ctrl:1
	v_add_f32_e32 v8, v4, v5
	ds_read_b128 v[168:171], v30 offset:4096
	v_add_f32_dpp v2, v2, v2 quad_perm:[2,3,0,1] row_mask:0xf bank_mask:0xf bound_ctrl:1
	ds_read_b128 v[172:175], v30 offset:4352
	ds_read_b128 v[176:179], v30 offset:4608
	v_add_f32_dpp v2, v2, v2 row_half_mirror row_mask:0xf bank_mask:0xf bound_ctrl:1
	ds_read_b128 v[180:183], v30 offset:4864
	v_add_f32_dpp v6, v7, v6 quad_perm:[1,0,3,2] row_mask:0xf bank_mask:0xf bound_ctrl:1
	v_add_f32_dpp v2, v2, v2 row_mirror row_mask:0xf bank_mask:0xf bound_ctrl:1
	v_add_f32_dpp v55, v57, v55 quad_perm:[1,0,3,2] row_mask:0xf bank_mask:0xf bound_ctrl:1
	v_cndmask_b32_e64 v57, v6, v55, s[14:15]
	v_cndmask_b32_e64 v7, v55, v6, s[14:15]
	v_pk_fma_f32 v[16:17], v[2:3], v[196:197], v[16:17] op_sel_hi:[0,1,1] neg_lo:[1,0,0] neg_hi:[1,0,0]
	v_pk_fma_f32 v[18:19], v[2:3], v[198:199], v[18:19] op_sel_hi:[0,1,1] neg_lo:[1,0,0] neg_hi:[1,0,0]
	s_waitcnt lgkmcnt(4)
	v_pk_mul_f32 v[0:1], v[16:17], v[208:209]
	v_pk_fma_f32 v[12:13], v[66:67], v[204:205], v[16:17] op_sel_hi:[0,1,1]
	v_pk_fma_f32 v[0:1], v[18:19], v[210:211], v[0:1]
	v_pk_fma_f32 v[14:15], v[66:67], v[206:207], v[18:19] op_sel_hi:[0,1,1]
	v_add_f32_e32 v2, v0, v1
	v_pk_mul_f32 v[4:5], v[184:185], v[16:17]
	v_pk_fma_f32 v[4:5], v[18:19], v[186:187], v[4:5]
	v_add_f32_dpp v2, v2, v2 quad_perm:[1,0,3,2] row_mask:0xf bank_mask:0xf bound_ctrl:1
	v_add_f32_e32 v9, v4, v5
	ds_read_b128 v[184:187], v30 offset:5120
	v_add_f32_dpp v2, v2, v2 quad_perm:[2,3,0,1] row_mask:0xf bank_mask:0xf bound_ctrl:1
	ds_read_b128 v[188:191], v30 offset:5376
	ds_read_b128 v[192:195], v30 offset:5632
	v_add_f32_dpp v2, v2, v2 row_half_mirror row_mask:0xf bank_mask:0xf bound_ctrl:1
	ds_read_b128 v[196:199], v30 offset:5888
	v_add_f32_dpp v7, v57, v7 quad_perm:[2,3,0,1] row_mask:0xf bank_mask:0xf bound_ctrl:1
	v_add_f32_dpp v2, v2, v2 row_mirror row_mask:0xf bank_mask:0xf bound_ctrl:1
	ds_read_b128 v[104:107], v49 offset:16
	v_add_f32_dpp v7, v7, v7 row_ror:4 row_mask:0xf bank_mask:0xf bound_ctrl:1
	v_pk_fma_f32 v[12:13], v[2:3], v[212:213], v[12:13] op_sel_hi:[0,1,1] neg_lo:[1,0,0] neg_hi:[1,0,0]
	v_pk_fma_f32 v[14:15], v[2:3], v[214:215], v[14:15] op_sel_hi:[0,1,1] neg_lo:[1,0,0] neg_hi:[1,0,0]
	v_pk_mul_f32 v[0:1], v[12:13], v[224:225]
	v_pk_fma_f32 v[16:17], v[66:67], v[220:221], v[12:13] op_sel:[1,0,0]
	v_pk_fma_f32 v[0:1], v[14:15], v[226:227], v[0:1]
	v_pk_fma_f32 v[18:19], v[66:67], v[222:223], v[14:15] op_sel:[1,0,0]
	v_add_f32_e32 v2, v0, v1
	v_pk_mul_f32 v[4:5], v[200:201], v[12:13]
	v_pk_fma_f32 v[4:5], v[14:15], v[202:203], v[4:5]
	v_add_f32_dpp v2, v2, v2 quad_perm:[1,0,3,2] row_mask:0xf bank_mask:0xf bound_ctrl:1
	v_add_f32_e32 v10, v4, v5
	ds_read_b128 v[200:203], v30 offset:6144
	v_add_f32_dpp v2, v2, v2 quad_perm:[2,3,0,1] row_mask:0xf bank_mask:0xf bound_ctrl:1
	ds_read_b128 v[204:207], v30 offset:6400
	ds_read_b128 v[208:211], v30 offset:6656
	v_add_f32_dpp v2, v2, v2 row_half_mirror row_mask:0xf bank_mask:0xf bound_ctrl:1
	ds_read_b128 v[212:215], v30 offset:6912
	v_add_f32_dpp v7, v7, v7 row_ror:8 row_mask:0xf bank_mask:0xf bound_ctrl:1
	v_add_f32_dpp v2, v2, v2 row_mirror row_mask:0xf bank_mask:0xf bound_ctrl:1
	ds_write_b32 v53, v7 offset:256
	v_add_u32_e32 v53, 0x200, v53
	v_pk_fma_f32 v[16:17], v[2:3], v[228:229], v[16:17] op_sel_hi:[0,1,1] neg_lo:[1,0,0] neg_hi:[1,0,0]
	v_pk_fma_f32 v[18:19], v[2:3], v[230:231], v[18:19] op_sel_hi:[0,1,1] neg_lo:[1,0,0] neg_hi:[1,0,0]
	s_waitcnt lgkmcnt(5)
	v_pk_mul_f32 v[0:1], v[16:17], v[176:177]
	v_pk_fma_f32 v[12:13], v[104:105], v[172:173], v[16:17] op_sel_hi:[0,1,1]
	v_pk_fma_f32 v[0:1], v[18:19], v[178:179], v[0:1]
	v_pk_fma_f32 v[14:15], v[104:105], v[174:175], v[18:19] op_sel_hi:[0,1,1]
	v_add_f32_e32 v2, v0, v1
	v_pk_mul_f32 v[4:5], v[216:217], v[16:17]
	v_pk_fma_f32 v[4:5], v[18:19], v[218:219], v[4:5]
	v_add_f32_dpp v2, v2, v2 quad_perm:[1,0,3,2] row_mask:0xf bank_mask:0xf bound_ctrl:1
	v_add_f32_e32 v11, v4, v5
	ds_read_b128 v[216:219], v30 offset:7168
	v_add_f32_dpp v2, v2, v2 quad_perm:[2,3,0,1] row_mask:0xf bank_mask:0xf bound_ctrl:1
	ds_read_b128 v[220:223], v30 offset:7424
	ds_read_b128 v[224:227], v30 offset:7680
	v_add_f32_dpp v2, v2, v2 row_half_mirror row_mask:0xf bank_mask:0xf bound_ctrl:1
	ds_read_b128 v[228:231], v30 offset:7936
	v_cndmask_b32_e64 v6, v9, v8, s[12:13]
	v_add_f32_dpp v2, v2, v2 row_mirror row_mask:0xf bank_mask:0xf bound_ctrl:1
	v_cndmask_b32_e64 v7, v8, v9, s[12:13]
	v_cndmask_b32_e64 v55, v11, v10, s[12:13]
	v_cndmask_b32_e64 v57, v10, v11, s[12:13]
	v_pk_fma_f32 v[12:13], v[2:3], v[180:181], v[12:13] op_sel_hi:[0,1,1] neg_lo:[1,0,0] neg_hi:[1,0,0]
	v_pk_fma_f32 v[14:15], v[2:3], v[182:183], v[14:15] op_sel_hi:[0,1,1] neg_lo:[1,0,0] neg_hi:[1,0,0]
	v_pk_mul_f32 v[0:1], v[12:13], v[192:193]
	v_pk_fma_f32 v[16:17], v[104:105], v[188:189], v[12:13] op_sel:[1,0,0]
	v_pk_fma_f32 v[0:1], v[14:15], v[194:195], v[0:1]
	v_pk_fma_f32 v[18:19], v[104:105], v[190:191], v[14:15] op_sel:[1,0,0]
	v_add_f32_e32 v2, v0, v1
	v_pk_mul_f32 v[4:5], v[168:169], v[12:13]
	v_pk_fma_f32 v[4:5], v[14:15], v[170:171], v[4:5]
	v_add_f32_dpp v2, v2, v2 quad_perm:[1,0,3,2] row_mask:0xf bank_mask:0xf bound_ctrl:1
	v_add_f32_e32 v24, v4, v5
	ds_read_b128 v[168:171], v30 offset:8192
	v_add_f32_dpp v2, v2, v2 quad_perm:[2,3,0,1] row_mask:0xf bank_mask:0xf bound_ctrl:1
	ds_read_b128 v[172:175], v30 offset:8448
	ds_read_b128 v[176:179], v30 offset:8704
	v_add_f32_dpp v2, v2, v2 row_half_mirror row_mask:0xf bank_mask:0xf bound_ctrl:1
	ds_read_b128 v[180:183], v30 offset:8960
	v_add_f32_dpp v6, v7, v6 quad_perm:[1,0,3,2] row_mask:0xf bank_mask:0xf bound_ctrl:1
	v_add_f32_dpp v2, v2, v2 row_mirror row_mask:0xf bank_mask:0xf bound_ctrl:1
	v_add_f32_dpp v55, v57, v55 quad_perm:[1,0,3,2] row_mask:0xf bank_mask:0xf bound_ctrl:1
	v_cndmask_b32_e64 v57, v6, v55, s[14:15]
	v_cndmask_b32_e64 v7, v55, v6, s[14:15]
	v_pk_fma_f32 v[16:17], v[2:3], v[196:197], v[16:17] op_sel_hi:[0,1,1] neg_lo:[1,0,0] neg_hi:[1,0,0]
	v_pk_fma_f32 v[18:19], v[2:3], v[198:199], v[18:19] op_sel_hi:[0,1,1] neg_lo:[1,0,0] neg_hi:[1,0,0]
	s_waitcnt lgkmcnt(4)
	v_pk_mul_f32 v[0:1], v[16:17], v[208:209]
	v_pk_fma_f32 v[12:13], v[106:107], v[204:205], v[16:17] op_sel_hi:[0,1,1]
	v_pk_fma_f32 v[0:1], v[18:19], v[210:211], v[0:1]
	v_pk_fma_f32 v[14:15], v[106:107], v[206:207], v[18:19] op_sel_hi:[0,1,1]
	v_add_f32_e32 v2, v0, v1
	v_pk_mul_f32 v[4:5], v[184:185], v[16:17]
	v_pk_fma_f32 v[4:5], v[18:19], v[186:187], v[4:5]
	v_add_f32_dpp v2, v2, v2 quad_perm:[1,0,3,2] row_mask:0xf bank_mask:0xf bound_ctrl:1
	v_add_f32_e32 v25, v4, v5
	ds_read_b128 v[184:187], v30 offset:9216
	v_add_f32_dpp v2, v2, v2 quad_perm:[2,3,0,1] row_mask:0xf bank_mask:0xf bound_ctrl:1
	ds_read_b128 v[188:191], v30 offset:9472
	ds_read_b128 v[192:195], v30 offset:9728
	v_add_f32_dpp v2, v2, v2 row_half_mirror row_mask:0xf bank_mask:0xf bound_ctrl:1
	ds_read_b128 v[196:199], v30 offset:9984
	v_add_f32_dpp v7, v57, v7 quad_perm:[2,3,0,1] row_mask:0xf bank_mask:0xf bound_ctrl:1
	v_add_f32_dpp v2, v2, v2 row_mirror row_mask:0xf bank_mask:0xf bound_ctrl:1
	ds_read_b128 v[64:67], v49 offset:32
	v_add_u32_e32 v49, 32, v49
	v_add_f32_dpp v7, v7, v7 row_ror:4 row_mask:0xf bank_mask:0xf bound_ctrl:1
	v_pk_fma_f32 v[12:13], v[2:3], v[212:213], v[12:13] op_sel_hi:[0,1,1] neg_lo:[1,0,0] neg_hi:[1,0,0]
	v_pk_fma_f32 v[14:15], v[2:3], v[214:215], v[14:15] op_sel_hi:[0,1,1] neg_lo:[1,0,0] neg_hi:[1,0,0]
	v_pk_mul_f32 v[0:1], v[12:13], v[224:225]
	v_pk_fma_f32 v[16:17], v[106:107], v[220:221], v[12:13] op_sel:[1,0,0]
	v_pk_fma_f32 v[0:1], v[14:15], v[226:227], v[0:1]
	v_pk_fma_f32 v[18:19], v[106:107], v[222:223], v[14:15] op_sel:[1,0,0]
	v_add_f32_e32 v2, v0, v1
	v_pk_mul_f32 v[4:5], v[200:201], v[12:13]
	v_pk_fma_f32 v[4:5], v[14:15], v[202:203], v[4:5]
	v_add_f32_dpp v2, v2, v2 quad_perm:[1,0,3,2] row_mask:0xf bank_mask:0xf bound_ctrl:1
	v_add_f32_e32 v26, v4, v5
	ds_read_b128 v[200:203], v30 offset:10240
	v_add_f32_dpp v2, v2, v2 quad_perm:[2,3,0,1] row_mask:0xf bank_mask:0xf bound_ctrl:1
	ds_read_b128 v[204:207], v30 offset:10496
	ds_read_b128 v[208:211], v30 offset:10752
	v_add_f32_dpp v2, v2, v2 row_half_mirror row_mask:0xf bank_mask:0xf bound_ctrl:1
	ds_read_b128 v[212:215], v30 offset:11008
	v_add_f32_dpp v7, v7, v7 row_ror:8 row_mask:0xf bank_mask:0xf bound_ctrl:1
	v_add_f32_dpp v2, v2, v2 row_mirror row_mask:0xf bank_mask:0xf bound_ctrl:1
	ds_write_b32 v53, v7
	v_pk_fma_f32 v[16:17], v[2:3], v[228:229], v[16:17] op_sel_hi:[0,1,1] neg_lo:[1,0,0] neg_hi:[1,0,0]
	v_pk_fma_f32 v[18:19], v[2:3], v[230:231], v[18:19] op_sel_hi:[0,1,1] neg_lo:[1,0,0] neg_hi:[1,0,0]
	v_add_u32_e32 v30, 0x2000, v30
	s_waitcnt lgkmcnt(5)
	v_pk_mul_f32 v[0:1], v[16:17], v[176:177]
	v_pk_fma_f32 v[12:13], v[64:65], v[172:173], v[16:17] op_sel_hi:[0,1,1]
	v_pk_fma_f32 v[0:1], v[18:19], v[178:179], v[0:1]
	v_pk_fma_f32 v[14:15], v[64:65], v[174:175], v[18:19] op_sel_hi:[0,1,1]
	v_add_f32_e32 v2, v0, v1
	v_pk_mul_f32 v[4:5], v[216:217], v[16:17]
	v_pk_fma_f32 v[4:5], v[18:19], v[218:219], v[4:5]
	v_add_f32_dpp v2, v2, v2 quad_perm:[1,0,3,2] row_mask:0xf bank_mask:0xf bound_ctrl:1
	v_add_f32_e32 v27, v4, v5
	ds_read_b128 v[216:219], v30 offset:3072
	v_add_f32_dpp v2, v2, v2 quad_perm:[2,3,0,1] row_mask:0xf bank_mask:0xf bound_ctrl:1
	ds_read_b128 v[220:223], v30 offset:3328
	ds_read_b128 v[224:227], v30 offset:3584
	v_add_f32_dpp v2, v2, v2 row_half_mirror row_mask:0xf bank_mask:0xf bound_ctrl:1
	ds_read_b128 v[228:231], v30 offset:3840
	v_cndmask_b32_e64 v6, v25, v24, s[12:13]
	v_add_f32_dpp v2, v2, v2 row_mirror row_mask:0xf bank_mask:0xf bound_ctrl:1
	v_cndmask_b32_e64 v7, v24, v25, s[12:13]
	v_cndmask_b32_e64 v55, v27, v26, s[12:13]
	v_cndmask_b32_e64 v57, v26, v27, s[12:13]
	v_pk_fma_f32 v[12:13], v[2:3], v[180:181], v[12:13] op_sel_hi:[0,1,1] neg_lo:[1,0,0] neg_hi:[1,0,0]
	v_pk_fma_f32 v[14:15], v[2:3], v[182:183], v[14:15] op_sel_hi:[0,1,1] neg_lo:[1,0,0] neg_hi:[1,0,0]
	v_pk_mul_f32 v[0:1], v[12:13], v[192:193]
	v_pk_fma_f32 v[16:17], v[64:65], v[188:189], v[12:13] op_sel:[1,0,0]
	v_pk_fma_f32 v[0:1], v[14:15], v[194:195], v[0:1]
	v_pk_fma_f32 v[18:19], v[64:65], v[190:191], v[14:15] op_sel:[1,0,0]
	v_add_f32_e32 v2, v0, v1
	v_pk_mul_f32 v[4:5], v[168:169], v[12:13]
	v_pk_fma_f32 v[4:5], v[14:15], v[170:171], v[4:5]
	v_add_f32_dpp v2, v2, v2 quad_perm:[1,0,3,2] row_mask:0xf bank_mask:0xf bound_ctrl:1
	v_add_f32_e32 v8, v4, v5
	ds_read_b128 v[168:171], v30 offset:4096
	v_add_f32_dpp v2, v2, v2 quad_perm:[2,3,0,1] row_mask:0xf bank_mask:0xf bound_ctrl:1
	ds_read_b128 v[172:175], v30 offset:4352
	ds_read_b128 v[176:179], v30 offset:4608
	v_add_f32_dpp v2, v2, v2 row_half_mirror row_mask:0xf bank_mask:0xf bound_ctrl:1
	ds_read_b128 v[180:183], v30 offset:4864
	v_add_f32_dpp v6, v7, v6 quad_perm:[1,0,3,2] row_mask:0xf bank_mask:0xf bound_ctrl:1
	v_add_f32_dpp v2, v2, v2 row_mirror row_mask:0xf bank_mask:0xf bound_ctrl:1
	v_add_f32_dpp v55, v57, v55 quad_perm:[1,0,3,2] row_mask:0xf bank_mask:0xf bound_ctrl:1
	v_cndmask_b32_e64 v57, v6, v55, s[14:15]
	v_cndmask_b32_e64 v7, v55, v6, s[14:15]
	v_pk_fma_f32 v[16:17], v[2:3], v[196:197], v[16:17] op_sel_hi:[0,1,1] neg_lo:[1,0,0] neg_hi:[1,0,0]
	v_pk_fma_f32 v[18:19], v[2:3], v[198:199], v[18:19] op_sel_hi:[0,1,1] neg_lo:[1,0,0] neg_hi:[1,0,0]
	s_waitcnt lgkmcnt(4)
	v_pk_mul_f32 v[0:1], v[16:17], v[208:209]
	v_pk_fma_f32 v[12:13], v[66:67], v[204:205], v[16:17] op_sel_hi:[0,1,1]
	v_pk_fma_f32 v[0:1], v[18:19], v[210:211], v[0:1]
	v_pk_fma_f32 v[14:15], v[66:67], v[206:207], v[18:19] op_sel_hi:[0,1,1]
	v_add_f32_e32 v2, v0, v1
	v_pk_mul_f32 v[4:5], v[184:185], v[16:17]
	v_pk_fma_f32 v[4:5], v[18:19], v[186:187], v[4:5]
	v_add_f32_dpp v2, v2, v2 quad_perm:[1,0,3,2] row_mask:0xf bank_mask:0xf bound_ctrl:1
	v_add_f32_e32 v9, v4, v5
	ds_read_b128 v[184:187], v30 offset:5120
	v_add_f32_dpp v2, v2, v2 quad_perm:[2,3,0,1] row_mask:0xf bank_mask:0xf bound_ctrl:1
	ds_read_b128 v[188:191], v30 offset:5376
	ds_read_b128 v[192:195], v30 offset:5632
	v_add_f32_dpp v2, v2, v2 row_half_mirror row_mask:0xf bank_mask:0xf bound_ctrl:1
	ds_read_b128 v[196:199], v30 offset:5888
	v_add_f32_dpp v7, v57, v7 quad_perm:[2,3,0,1] row_mask:0xf bank_mask:0xf bound_ctrl:1
	v_add_f32_dpp v2, v2, v2 row_mirror row_mask:0xf bank_mask:0xf bound_ctrl:1
	ds_read_b128 v[104:107], v49 offset:16
	v_add_f32_dpp v7, v7, v7 row_ror:4 row_mask:0xf bank_mask:0xf bound_ctrl:1
	v_pk_fma_f32 v[12:13], v[2:3], v[212:213], v[12:13] op_sel_hi:[0,1,1] neg_lo:[1,0,0] neg_hi:[1,0,0]
	v_pk_fma_f32 v[14:15], v[2:3], v[214:215], v[14:15] op_sel_hi:[0,1,1] neg_lo:[1,0,0] neg_hi:[1,0,0]
	v_pk_mul_f32 v[0:1], v[12:13], v[224:225]
	v_pk_fma_f32 v[16:17], v[66:67], v[220:221], v[12:13] op_sel:[1,0,0]
	v_pk_fma_f32 v[0:1], v[14:15], v[226:227], v[0:1]
	v_pk_fma_f32 v[18:19], v[66:67], v[222:223], v[14:15] op_sel:[1,0,0]
	v_add_f32_e32 v2, v0, v1
	v_pk_mul_f32 v[4:5], v[200:201], v[12:13]
	v_pk_fma_f32 v[4:5], v[14:15], v[202:203], v[4:5]
	v_add_f32_dpp v2, v2, v2 quad_perm:[1,0,3,2] row_mask:0xf bank_mask:0xf bound_ctrl:1
	v_add_f32_e32 v10, v4, v5
	ds_read_b128 v[200:203], v30 offset:6144
	v_add_f32_dpp v2, v2, v2 quad_perm:[2,3,0,1] row_mask:0xf bank_mask:0xf bound_ctrl:1
	ds_read_b128 v[204:207], v30 offset:6400
	ds_read_b128 v[208:211], v30 offset:6656
	v_add_f32_dpp v2, v2, v2 row_half_mirror row_mask:0xf bank_mask:0xf bound_ctrl:1
	ds_read_b128 v[212:215], v30 offset:6912
	v_add_f32_dpp v7, v7, v7 row_ror:8 row_mask:0xf bank_mask:0xf bound_ctrl:1
	v_add_f32_dpp v2, v2, v2 row_mirror row_mask:0xf bank_mask:0xf bound_ctrl:1
	ds_write_b32 v53, v7 offset:256
	v_add_u32_e32 v53, 0x200, v53
	v_pk_fma_f32 v[16:17], v[2:3], v[228:229], v[16:17] op_sel_hi:[0,1,1] neg_lo:[1,0,0] neg_hi:[1,0,0]
	v_pk_fma_f32 v[18:19], v[2:3], v[230:231], v[18:19] op_sel_hi:[0,1,1] neg_lo:[1,0,0] neg_hi:[1,0,0]
	s_waitcnt lgkmcnt(5)
	v_pk_mul_f32 v[0:1], v[16:17], v[176:177]
	v_pk_fma_f32 v[12:13], v[104:105], v[172:173], v[16:17] op_sel_hi:[0,1,1]
	v_pk_fma_f32 v[0:1], v[18:19], v[178:179], v[0:1]
	v_pk_fma_f32 v[14:15], v[104:105], v[174:175], v[18:19] op_sel_hi:[0,1,1]
	v_add_f32_e32 v2, v0, v1
	v_pk_mul_f32 v[4:5], v[216:217], v[16:17]
	v_pk_fma_f32 v[4:5], v[18:19], v[218:219], v[4:5]
	v_add_f32_dpp v2, v2, v2 quad_perm:[1,0,3,2] row_mask:0xf bank_mask:0xf bound_ctrl:1
	v_add_f32_e32 v11, v4, v5
	ds_read_b128 v[216:219], v30 offset:7168
	v_add_f32_dpp v2, v2, v2 quad_perm:[2,3,0,1] row_mask:0xf bank_mask:0xf bound_ctrl:1
	ds_read_b128 v[220:223], v30 offset:7424
	ds_read_b128 v[224:227], v30 offset:7680
	v_add_f32_dpp v2, v2, v2 row_half_mirror row_mask:0xf bank_mask:0xf bound_ctrl:1
	ds_read_b128 v[228:231], v30 offset:7936
	v_cndmask_b32_e64 v6, v9, v8, s[12:13]
	v_add_f32_dpp v2, v2, v2 row_mirror row_mask:0xf bank_mask:0xf bound_ctrl:1
	v_cndmask_b32_e64 v7, v8, v9, s[12:13]
	v_cndmask_b32_e64 v55, v11, v10, s[12:13]
	v_cndmask_b32_e64 v57, v10, v11, s[12:13]
	v_pk_fma_f32 v[12:13], v[2:3], v[180:181], v[12:13] op_sel_hi:[0,1,1] neg_lo:[1,0,0] neg_hi:[1,0,0]
	v_pk_fma_f32 v[14:15], v[2:3], v[182:183], v[14:15] op_sel_hi:[0,1,1] neg_lo:[1,0,0] neg_hi:[1,0,0]
	v_pk_mul_f32 v[0:1], v[12:13], v[192:193]
	v_pk_fma_f32 v[16:17], v[104:105], v[188:189], v[12:13] op_sel:[1,0,0]
	v_pk_fma_f32 v[0:1], v[14:15], v[194:195], v[0:1]
	v_pk_fma_f32 v[18:19], v[104:105], v[190:191], v[14:15] op_sel:[1,0,0]
	v_add_f32_e32 v2, v0, v1
	v_pk_mul_f32 v[4:5], v[168:169], v[12:13]
	v_pk_fma_f32 v[4:5], v[14:15], v[170:171], v[4:5]
	v_add_f32_dpp v2, v2, v2 quad_perm:[1,0,3,2] row_mask:0xf bank_mask:0xf bound_ctrl:1
	v_add_f32_e32 v24, v4, v5
	ds_read_b128 v[168:171], v30 offset:8192
	v_add_f32_dpp v2, v2, v2 quad_perm:[2,3,0,1] row_mask:0xf bank_mask:0xf bound_ctrl:1
	ds_read_b128 v[172:175], v30 offset:8448
	ds_read_b128 v[176:179], v30 offset:8704
	v_add_f32_dpp v2, v2, v2 row_half_mirror row_mask:0xf bank_mask:0xf bound_ctrl:1
	ds_read_b128 v[180:183], v30 offset:8960
	v_add_f32_dpp v6, v7, v6 quad_perm:[1,0,3,2] row_mask:0xf bank_mask:0xf bound_ctrl:1
	v_add_f32_dpp v2, v2, v2 row_mirror row_mask:0xf bank_mask:0xf bound_ctrl:1
	v_add_f32_dpp v55, v57, v55 quad_perm:[1,0,3,2] row_mask:0xf bank_mask:0xf bound_ctrl:1
	v_cndmask_b32_e64 v57, v6, v55, s[14:15]
	v_cndmask_b32_e64 v7, v55, v6, s[14:15]
	v_pk_fma_f32 v[16:17], v[2:3], v[196:197], v[16:17] op_sel_hi:[0,1,1] neg_lo:[1,0,0] neg_hi:[1,0,0]
	v_pk_fma_f32 v[18:19], v[2:3], v[198:199], v[18:19] op_sel_hi:[0,1,1] neg_lo:[1,0,0] neg_hi:[1,0,0]
	s_waitcnt lgkmcnt(4)
	v_pk_mul_f32 v[0:1], v[16:17], v[208:209]
	v_pk_fma_f32 v[12:13], v[106:107], v[204:205], v[16:17] op_sel_hi:[0,1,1]
	v_pk_fma_f32 v[0:1], v[18:19], v[210:211], v[0:1]
	v_pk_fma_f32 v[14:15], v[106:107], v[206:207], v[18:19] op_sel_hi:[0,1,1]
	v_add_f32_e32 v2, v0, v1
	v_pk_mul_f32 v[4:5], v[184:185], v[16:17]
	v_pk_fma_f32 v[4:5], v[18:19], v[186:187], v[4:5]
	v_add_f32_dpp v2, v2, v2 quad_perm:[1,0,3,2] row_mask:0xf bank_mask:0xf bound_ctrl:1
	v_add_f32_e32 v25, v4, v5
	ds_read_b128 v[184:187], v30 offset:9216
	v_add_f32_dpp v2, v2, v2 quad_perm:[2,3,0,1] row_mask:0xf bank_mask:0xf bound_ctrl:1
	ds_read_b128 v[188:191], v30 offset:9472
	ds_read_b128 v[192:195], v30 offset:9728
	v_add_f32_dpp v2, v2, v2 row_half_mirror row_mask:0xf bank_mask:0xf bound_ctrl:1
	ds_read_b128 v[196:199], v30 offset:9984
	v_add_f32_dpp v7, v57, v7 quad_perm:[2,3,0,1] row_mask:0xf bank_mask:0xf bound_ctrl:1
	v_add_f32_dpp v2, v2, v2 row_mirror row_mask:0xf bank_mask:0xf bound_ctrl:1
	ds_read_b128 v[64:67], v49 offset:32
	v_add_u32_e32 v49, 32, v49
	v_add_f32_dpp v7, v7, v7 row_ror:4 row_mask:0xf bank_mask:0xf bound_ctrl:1
	v_pk_fma_f32 v[12:13], v[2:3], v[212:213], v[12:13] op_sel_hi:[0,1,1] neg_lo:[1,0,0] neg_hi:[1,0,0]
	v_pk_fma_f32 v[14:15], v[2:3], v[214:215], v[14:15] op_sel_hi:[0,1,1] neg_lo:[1,0,0] neg_hi:[1,0,0]
	v_pk_mul_f32 v[0:1], v[12:13], v[224:225]
	v_pk_fma_f32 v[16:17], v[106:107], v[220:221], v[12:13] op_sel:[1,0,0]
	v_pk_fma_f32 v[0:1], v[14:15], v[226:227], v[0:1]
	v_pk_fma_f32 v[18:19], v[106:107], v[222:223], v[14:15] op_sel:[1,0,0]
	v_add_f32_e32 v2, v0, v1
	v_pk_mul_f32 v[4:5], v[200:201], v[12:13]
	v_pk_fma_f32 v[4:5], v[14:15], v[202:203], v[4:5]
	v_add_f32_dpp v2, v2, v2 quad_perm:[1,0,3,2] row_mask:0xf bank_mask:0xf bound_ctrl:1
	v_add_f32_e32 v26, v4, v5
	ds_read_b128 v[200:203], v30 offset:10240
	v_add_f32_dpp v2, v2, v2 quad_perm:[2,3,0,1] row_mask:0xf bank_mask:0xf bound_ctrl:1
	ds_read_b128 v[204:207], v30 offset:10496
	ds_read_b128 v[208:211], v30 offset:10752
	v_add_f32_dpp v2, v2, v2 row_half_mirror row_mask:0xf bank_mask:0xf bound_ctrl:1
	ds_read_b128 v[212:215], v30 offset:11008
	v_add_f32_dpp v7, v7, v7 row_ror:8 row_mask:0xf bank_mask:0xf bound_ctrl:1
	v_add_f32_dpp v2, v2, v2 row_mirror row_mask:0xf bank_mask:0xf bound_ctrl:1
	ds_write_b32 v53, v7
	v_pk_fma_f32 v[16:17], v[2:3], v[228:229], v[16:17] op_sel_hi:[0,1,1] neg_lo:[1,0,0] neg_hi:[1,0,0]
	v_pk_fma_f32 v[18:19], v[2:3], v[230:231], v[18:19] op_sel_hi:[0,1,1] neg_lo:[1,0,0] neg_hi:[1,0,0]
	v_add_u32_e32 v30, 0x2000, v30
.LrwT_last:
	s_waitcnt lgkmcnt(5)
	v_pk_mul_f32 v[0:1], v[16:17], v[176:177]
	v_pk_fma_f32 v[12:13], v[64:65], v[172:173], v[16:17] op_sel_hi:[0,1,1]
	v_pk_fma_f32 v[0:1], v[18:19], v[178:179], v[0:1]
	v_pk_fma_f32 v[14:15], v[64:65], v[174:175], v[18:19] op_sel_hi:[0,1,1]
	v_add_f32_e32 v2, v0, v1
	v_pk_mul_f32 v[4:5], v[216:217], v[16:17]
	v_pk_fma_f32 v[4:5], v[18:19], v[218:219], v[4:5]
	v_add_f32_dpp v2, v2, v2 quad_perm:[1,0,3,2] row_mask:0xf bank_mask:0xf bound_ctrl:1
	v_add_f32_e32 v27, v4, v5
	ds_read_b128 v[216:219], v30 offset:3072
	v_add_f32_dpp v2, v2, v2 quad_perm:[2,3,0,1] row_mask:0xf bank_mask:0xf bound_ctrl:1
	ds_read_b128 v[220:223], v30 offset:3328
	ds_read_b128 v[224:227], v30 offset:3584
	v_add_f32_dpp v2, v2, v2 row_half_mirror row_mask:0xf bank_mask:0xf bound_ctrl:1
	ds_read_b128 v[228:231], v30 offset:3840
	v_cndmask_b32_e64 v6, v25, v24, s[12:13]
	v_add_f32_dpp v2, v2, v2 row_mirror row_mask:0xf bank_mask:0xf bound_ctrl:1
	v_cndmask_b32_e64 v7, v24, v25, s[12:13]
	v_cndmask_b32_e64 v55, v27, v26, s[12:13]
	v_cndmask_b32_e64 v57, v26, v27, s[12:13]
	v_pk_fma_f32 v[12:13], v[2:3], v[180:181], v[12:13] op_sel_hi:[0,1,1] neg_lo:[1,0,0] neg_hi:[1,0,0]
	v_pk_fma_f32 v[14:15], v[2:3], v[182:183], v[14:15] op_sel_hi:[0,1,1] neg_lo:[1,0,0] neg_hi:[1,0,0]
	v_pk_mul_f32 v[0:1], v[12:13], v[192:193]
	v_pk_fma_f32 v[16:17], v[64:65], v[188:189], v[12:13] op_sel:[1,0,0]
	v_pk_fma_f32 v[0:1], v[14:15], v[194:195], v[0:1]
	v_pk_fma_f32 v[18:19], v[64:65], v[190:191], v[14:15] op_sel:[1,0,0]
	v_add_f32_e32 v2, v0, v1
	v_pk_mul_f32 v[4:5], v[168:169], v[12:13]
	v_pk_fma_f32 v[4:5], v[14:15], v[170:171], v[4:5]
	v_add_f32_dpp v2, v2, v2 quad_perm:[1,0,3,2] row_mask:0xf bank_mask:0xf bound_ctrl:1
	v_add_f32_e32 v8, v4, v5
	ds_read_b128 v[168:171], v30 offset:4096
	v_add_f32_dpp v2, v2, v2 quad_perm:[2,3,0,1] row_mask:0xf bank_mask:0xf bound_ctrl:1
	ds_read_b128 v[172:175], v30 offset:4352
	ds_read_b128 v[176:179], v30 offset:4608
	v_add_f32_dpp v2, v2, v2 row_half_mirror row_mask:0xf bank_mask:0xf bound_ctrl:1
	ds_read_b128 v[180:183], v30 offset:4864
	v_add_f32_dpp v6, v7, v6 quad_perm:[1,0,3,2] row_mask:0xf bank_mask:0xf bound_ctrl:1
	v_add_f32_dpp v2, v2, v2 row_mirror row_mask:0xf bank_mask:0xf bound_ctrl:1
	v_add_f32_dpp v55, v57, v55 quad_perm:[1,0,3,2] row_mask:0xf bank_mask:0xf bound_ctrl:1
	v_cndmask_b32_e64 v57, v6, v55, s[14:15]
	v_cndmask_b32_e64 v7, v55, v6, s[14:15]
	v_pk_fma_f32 v[16:17], v[2:3], v[196:197], v[16:17] op_sel_hi:[0,1,1] neg_lo:[1,0,0] neg_hi:[1,0,0]
	v_pk_fma_f32 v[18:19], v[2:3], v[198:199], v[18:19] op_sel_hi:[0,1,1] neg_lo:[1,0,0] neg_hi:[1,0,0]
	s_waitcnt lgkmcnt(4)
	v_pk_mul_f32 v[0:1], v[16:17], v[208:209]
	v_pk_fma_f32 v[12:13], v[66:67], v[204:205], v[16:17] op_sel_hi:[0,1,1]
	v_pk_fma_f32 v[0:1], v[18:19], v[210:211], v[0:1]
	v_pk_fma_f32 v[14:15], v[66:67], v[206:207], v[18:19] op_sel_hi:[0,1,1]
	v_add_f32_e32 v2, v0, v1
	v_pk_mul_f32 v[4:5], v[184:185], v[16:17]
	v_pk_fma_f32 v[4:5], v[18:19], v[186:187], v[4:5]
	v_add_f32_dpp v2, v2, v2 quad_perm:[1,0,3,2] row_mask:0xf bank_mask:0xf bound_ctrl:1
	v_add_f32_e32 v9, v4, v5
	ds_read_b128 v[184:187], v30 offset:5120
	v_add_f32_dpp v2, v2, v2 quad_perm:[2,3,0,1] row_mask:0xf bank_mask:0xf bound_ctrl:1
	ds_read_b128 v[188:191], v30 offset:5376
	ds_read_b128 v[192:195], v30 offset:5632
	v_add_f32_dpp v2, v2, v2 row_half_mirror row_mask:0xf bank_mask:0xf bound_ctrl:1
	ds_read_b128 v[196:199], v30 offset:5888
	v_add_f32_dpp v7, v57, v7 quad_perm:[2,3,0,1] row_mask:0xf bank_mask:0xf bound_ctrl:1
	v_add_f32_dpp v2, v2, v2 row_mirror row_mask:0xf bank_mask:0xf bound_ctrl:1
	ds_read_b128 v[104:107], v49 offset:16
	v_add_f32_dpp v7, v7, v7 row_ror:4 row_mask:0xf bank_mask:0xf bound_ctrl:1
	v_pk_fma_f32 v[12:13], v[2:3], v[212:213], v[12:13] op_sel_hi:[0,1,1] neg_lo:[1,0,0] neg_hi:[1,0,0]
	v_pk_fma_f32 v[14:15], v[2:3], v[214:215], v[14:15] op_sel_hi:[0,1,1] neg_lo:[1,0,0] neg_hi:[1,0,0]
	v_pk_mul_f32 v[0:1], v[12:13], v[224:225]
	v_pk_fma_f32 v[16:17], v[66:67], v[220:221], v[12:13] op_sel:[1,0,0]
	v_pk_fma_f32 v[0:1], v[14:15], v[226:227], v[0:1]
	v_pk_fma_f32 v[18:19], v[66:67], v[222:223], v[14:15] op_sel:[1,0,0]
	v_add_f32_e32 v2, v0, v1
	v_pk_mul_f32 v[4:5], v[200:201], v[12:13]
	v_pk_fma_f32 v[4:5], v[14:15], v[202:203], v[4:5]
	v_add_f32_dpp v2, v2, v2 quad_perm:[1,0,3,2] row_mask:0xf bank_mask:0xf bound_ctrl:1
	v_add_f32_e32 v10, v4, v5
	ds_read_b128 v[200:203], v30 offset:6144
	v_add_f32_dpp v2, v2, v2 quad_perm:[2,3,0,1] row_mask:0xf bank_mask:0xf bound_ctrl:1
	ds_read_b128 v[204:207], v30 offset:6400
	ds_read_b128 v[208:211], v30 offset:6656
	v_add_f32_dpp v2, v2, v2 row_half_mirror row_mask:0xf bank_mask:0xf bound_ctrl:1
	ds_read_b128 v[212:215], v30 offset:6912
	v_add_f32_dpp v7, v7, v7 row_ror:8 row_mask:0xf bank_mask:0xf bound_ctrl:1
	v_add_f32_dpp v2, v2, v2 row_mirror row_mask:0xf bank_mask:0xf bound_ctrl:1
	ds_write_b32 v53, v7 offset:256
	v_add_u32_e32 v53, 0x200, v53
	v_pk_fma_f32 v[16:17], v[2:3], v[228:229], v[16:17] op_sel_hi:[0,1,1] neg_lo:[1,0,0] neg_hi:[1,0,0]
	v_pk_fma_f32 v[18:19], v[2:3], v[230:231], v[18:19] op_sel_hi:[0,1,1] neg_lo:[1,0,0] neg_hi:[1,0,0]
	s_waitcnt lgkmcnt(5)
	v_pk_mul_f32 v[0:1], v[16:17], v[176:177]
	v_pk_fma_f32 v[12:13], v[104:105], v[172:173], v[16:17] op_sel_hi:[0,1,1]
	v_pk_fma_f32 v[0:1], v[18:19], v[178:179], v[0:1]
	v_pk_fma_f32 v[14:15], v[104:105], v[174:175], v[18:19] op_sel_hi:[0,1,1]
	v_add_f32_e32 v2, v0, v1
	v_pk_mul_f32 v[4:5], v[216:217], v[16:17]
	v_pk_fma_f32 v[4:5], v[18:19], v[218:219], v[4:5]
	v_add_f32_dpp v2, v2, v2 quad_perm:[1,0,3,2] row_mask:0xf bank_mask:0xf bound_ctrl:1
	v_add_f32_e32 v11, v4, v5
	ds_read_b128 v[216:219], v30 offset:7168
	v_add_f32_dpp v2, v2, v2 quad_perm:[2,3,0,1] row_mask:0xf bank_mask:0xf bound_ctrl:1
	ds_read_b128 v[220:223], v30 offset:7424
	ds_read_b128 v[224:227], v30 offset:7680
	v_add_f32_dpp v2, v2, v2 row_half_mirror row_mask:0xf bank_mask:0xf bound_ctrl:1
	ds_read_b128 v[228:231], v30 offset:7936
	v_cndmask_b32_e64 v6, v9, v8, s[12:13]
	v_add_f32_dpp v2, v2, v2 row_mirror row_mask:0xf bank_mask:0xf bound_ctrl:1
	v_cndmask_b32_e64 v7, v8, v9, s[12:13]
	v_cndmask_b32_e64 v55, v11, v10, s[12:13]
	v_cndmask_b32_e64 v57, v10, v11, s[12:13]
	v_pk_fma_f32 v[12:13], v[2:3], v[180:181], v[12:13] op_sel_hi:[0,1,1] neg_lo:[1,0,0] neg_hi:[1,0,0]
	v_pk_fma_f32 v[14:15], v[2:3], v[182:183], v[14:15] op_sel_hi:[0,1,1] neg_lo:[1,0,0] neg_hi:[1,0,0]
	v_pk_mul_f32 v[0:1], v[12:13], v[192:193]
	v_pk_fma_f32 v[16:17], v[104:105], v[188:189], v[12:13] op_sel:[1,0,0]
	v_pk_fma_f32 v[0:1], v[14:15], v[194:195], v[0:1]
	v_pk_fma_f32 v[18:19], v[104:105], v[190:191], v[14:15] op_sel:[1,0,0]
	v_add_f32_e32 v2, v0, v1
	v_pk_mul_f32 v[4:5], v[168:169], v[12:13]
	v_pk_fma_f32 v[4:5], v[14:15], v[170:171], v[4:5]
	v_add_f32_dpp v2, v2, v2 quad_perm:[1,0,3,2] row_mask:0xf bank_mask:0xf bound_ctrl:1
	v_add_f32_e32 v24, v4, v5
	s_nop 0
	v_add_f32_dpp v2, v2, v2 quad_perm:[2,3,0,1] row_mask:0xf bank_mask:0xf bound_ctrl:1
	s_nop 0
	s_nop 0
	v_add_f32_dpp v2, v2, v2 row_half_mirror row_mask:0xf bank_mask:0xf bound_ctrl:1
	s_nop 0
	v_add_f32_dpp v6, v7, v6 quad_perm:[1,0,3,2] row_mask:0xf bank_mask:0xf bound_ctrl:1
	v_add_f32_dpp v2, v2, v2 row_mirror row_mask:0xf bank_mask:0xf bound_ctrl:1
	v_add_f32_dpp v55, v57, v55 quad_perm:[1,0,3,2] row_mask:0xf bank_mask:0xf bound_ctrl:1
	v_cndmask_b32_e64 v57, v6, v55, s[14:15]
	v_cndmask_b32_e64 v7, v55, v6, s[14:15]
	v_pk_fma_f32 v[16:17], v[2:3], v[196:197], v[16:17] op_sel_hi:[0,1,1] neg_lo:[1,0,0] neg_hi:[1,0,0]
	v_pk_fma_f32 v[18:19], v[2:3], v[198:199], v[18:19] op_sel_hi:[0,1,1] neg_lo:[1,0,0] neg_hi:[1,0,0]
	s_waitcnt lgkmcnt(0)
	v_pk_mul_f32 v[0:1], v[16:17], v[208:209]
	v_pk_fma_f32 v[12:13], v[106:107], v[204:205], v[16:17] op_sel_hi:[0,1,1]
	v_pk_fma_f32 v[0:1], v[18:19], v[210:211], v[0:1]
	v_pk_fma_f32 v[14:15], v[106:107], v[206:207], v[18:19] op_sel_hi:[0,1,1]
	v_add_f32_e32 v2, v0, v1
	v_pk_mul_f32 v[4:5], v[184:185], v[16:17]
	v_pk_fma_f32 v[4:5], v[18:19], v[186:187], v[4:5]
	v_add_f32_dpp v2, v2, v2 quad_perm:[1,0,3,2] row_mask:0xf bank_mask:0xf bound_ctrl:1
	v_add_f32_e32 v25, v4, v5
	s_nop 0
	v_add_f32_dpp v2, v2, v2 quad_perm:[2,3,0,1] row_mask:0xf bank_mask:0xf bound_ctrl:1
	s_nop 0
	s_nop 0
	v_add_f32_dpp v2, v2, v2 row_half_mirror row_mask:0xf bank_mask:0xf bound_ctrl:1
	s_nop 0
	v_add_f32_dpp v7, v57, v7 quad_perm:[2,3,0,1] row_mask:0xf bank_mask:0xf bound_ctrl:1
	v_add_f32_dpp v2, v2, v2 row_mirror row_mask:0xf bank_mask:0xf bound_ctrl:1
	v_add_u32_e32 v49, 32, v49
	v_add_f32_dpp v7, v7, v7 row_ror:4 row_mask:0xf bank_mask:0xf bound_ctrl:1
	v_pk_fma_f32 v[12:13], v[2:3], v[212:213], v[12:13] op_sel_hi:[0,1,1] neg_lo:[1,0,0] neg_hi:[1,0,0]
	v_pk_fma_f32 v[14:15], v[2:3], v[214:215], v[14:15] op_sel_hi:[0,1,1] neg_lo:[1,0,0] neg_hi:[1,0,0]
	v_pk_mul_f32 v[0:1], v[12:13], v[224:225]
	v_pk_fma_f32 v[16:17], v[106:107], v[220:221], v[12:13] op_sel:[1,0,0]
	v_pk_fma_f32 v[0:1], v[14:15], v[226:227], v[0:1]
	v_pk_fma_f32 v[18:19], v[106:107], v[222:223], v[14:15] op_sel:[1,0,0]
	v_add_f32_e32 v2, v0, v1
	v_pk_mul_f32 v[4:5], v[200:201], v[12:13]
	v_pk_fma_f32 v[4:5], v[14:15], v[202:203], v[4:5]
	v_add_f32_dpp v2, v2, v2 quad_perm:[1,0,3,2] row_mask:0xf bank_mask:0xf bound_ctrl:1
	v_add_f32_e32 v26, v4, v5
	s_nop 0
	v_add_f32_dpp v2, v2, v2 quad_perm:[2,3,0,1] row_mask:0xf bank_mask:0xf bound_ctrl:1
	s_nop 0
	s_nop 0
	v_add_f32_dpp v2, v2, v2 row_half_mirror row_mask:0xf bank_mask:0xf bound_ctrl:1
	s_nop 0
	v_add_f32_dpp v7, v7, v7 row_ror:8 row_mask:0xf bank_mask:0xf bound_ctrl:1
	v_add_f32_dpp v2, v2, v2 row_mirror row_mask:0xf bank_mask:0xf bound_ctrl:1
	ds_write_b32 v53, v7
	v_pk_fma_f32 v[16:17], v[2:3], v[228:229], v[16:17] op_sel_hi:[0,1,1] neg_lo:[1,0,0] neg_hi:[1,0,0]
	v_pk_fma_f32 v[18:19], v[2:3], v[230:231], v[18:19] op_sel_hi:[0,1,1] neg_lo:[1,0,0] neg_hi:[1,0,0]
.LrwT_drain:
	v_pk_mul_f32 v[4:5], v[216:217], v[16:17]
	v_pk_fma_f32 v[4:5], v[18:19], v[218:219], v[4:5]
	s_nop 0
	v_add_f32_e32 v27, v4, v5
	v_cndmask_b32_e64 v6, v25, v24, s[12:13]
	v_cndmask_b32_e64 v7, v24, v25, s[12:13]
	v_cndmask_b32_e64 v55, v27, v26, s[12:13]
	v_cndmask_b32_e64 v57, v26, v27, s[12:13]
	v_add_f32_dpp v6, v7, v6 quad_perm:[1,0,3,2] row_mask:0xf bank_mask:0xf bound_ctrl:1
	v_pk_mul_f32 v[16:17], v[16:17], v[108:109]
	v_add_f32_dpp v55, v57, v55 quad_perm:[1,0,3,2] row_mask:0xf bank_mask:0xf bound_ctrl:1
	v_cndmask_b32_e64 v57, v6, v55, s[14:15]
	v_cndmask_b32_e64 v7, v55, v6, s[14:15]
	v_pk_mul_f32 v[18:19], v[18:19], v[110:111]
	v_add_f32_dpp v7, v57, v7 quad_perm:[2,3,0,1] row_mask:0xf bank_mask:0xf bound_ctrl:1
	s_add_i32 s26, s26, 1
	s_cmpk_eq_i32 s26, 0x201
	v_add_f32_dpp v7, v7, v7 row_ror:4 row_mask:0xf bank_mask:0xf bound_ctrl:1
	s_nop 1
	v_add_f32_dpp v7, v7, v7 row_ror:8 row_mask:0xf bank_mask:0xf bound_ctrl:1
	ds_write_b32 v53, v7 offset:256
	s_waitcnt lgkmcnt(0)
	s_barrier
	s_cbranch_scc0 .LrwT_tile
	s_lshl_b32 s22, s2, 14
	s_and_b32 s22, s22, 0x7c000
	s_add_u32 s22, s67, s22
	v_lshl_or_b32 v0, s47, 10, v70
	s_addc_u32 s23, s92, 0
	v_ashrrev_i32_e32 v1, 31, v0
	v_lshl_add_u64 v[0:1], v[0:1], 2, s[22:23]
	v_mov_b32_e32 v55, v31
	v_lshl_add_u64 v[0:1], v[0:1], 0, v[54:55]
	global_store_dwordx4 v[0:1], v[16:19], off
	s_branch .LBB0_451
